# DK=64 unbiased attention tiles (non-NA items): the four tail PV MFMAs of tile t deferred to the head of tile t+1 to cover the K-fragment LDS read latency
# baseline (speedup 1.0000x reference)
.LBB0_402:
	v_or_b32_e32 v2, s36, v10
	v_add_u32_e32 v2, s94, v2
	v_lshrrev_b32_e32 v5, 6, v2
	v_med3_u32 v5, v5, 4, 60
	v_add_u32_e32 v99, -4, v5
	v_add_u32_e32 v100, 4, v5
	v_lshrrev_b32_e32 v5, 1, v8
	v_bfe_u32 v7, v8, 1, 3
	v_bitop3_b32 v5, v9, v5, 7 bitop3:0x78
	v_lshlrev_b32_e32 v102, 4, v5
	v_bitop3_b32 v5, v9, v7, 2 bitop3:0x36
	v_and_b32_e32 v2, 63, v2
	v_lshlrev_b32_e32 v103, 4, v5
	v_bitop3_b32 v5, v9, v7, 4 bitop3:0x36
	v_med3_u32 v2, v2, 8, 56
	v_lshlrev_b32_e32 v104, 4, v5
	v_bitop3_b32 v5, v9, v7, 6 bitop3:0x36
	v_add_u32_e32 v6, -8, v2
	v_lshlrev_b32_e32 v105, 4, v5
	v_or_b32_e32 v5, 1, v98
	v_cmp_ge_u32_e64 s[4:5], v5, v6
	v_or_b32_e32 v5, 2, v98
	v_cmp_ge_u32_e64 s[6:7], v5, v6
	v_or_b32_e32 v5, 3, v98
	v_cmp_ge_u32_e64 s[8:9], v5, v6
	v_or_b32_e32 v5, 8, v98
	v_cmp_ge_u32_e64 s[10:11], v5, v6
	v_or_b32_e32 v5, 9, v98
	v_cmp_ge_u32_e64 s[12:13], v5, v6
	v_or_b32_e32 v5, 10, v98
	v_cmp_ge_u32_e64 s[14:15], v5, v6
	v_or_b32_e32 v5, 11, v98
	v_add_u32_e32 v2, 8, v2
	v_cmp_ge_u32_e64 s[16:17], v5, v6
	v_or_b32_e32 v5, 16, v98
	v_cmp_ge_u32_e32 vcc, v5, v6
	v_cmp_lt_u32_e64 s[18:19], v5, v2
	v_or_b32_e32 v5, 17, v98
	s_and_b64 s[52:53], vcc, s[18:19]
	v_cmp_ge_u32_e32 vcc, v5, v6
	v_cmp_lt_u32_e64 s[18:19], v5, v2
	v_or_b32_e32 v5, 18, v98
	s_and_b64 s[54:55], vcc, s[18:19]
	v_cmp_ge_u32_e32 vcc, v5, v6
	v_cmp_lt_u32_e64 s[18:19], v5, v2
	v_or_b32_e32 v5, 19, v98
	s_and_b64 s[56:57], vcc, s[18:19]
	v_cmp_ge_u32_e32 vcc, v5, v6
	v_cmp_lt_u32_e64 s[18:19], v5, v2
	v_or_b32_e32 v5, 24, v98
	s_and_b64 s[58:59], vcc, s[18:19]
	v_cmp_ge_u32_e32 vcc, v5, v6
	v_cmp_lt_u32_e64 s[18:19], v5, v2
	v_or_b32_e32 v5, 25, v98
	s_and_b64 s[60:61], vcc, s[18:19]
	v_cmp_ge_u32_e32 vcc, v5, v6
	v_cmp_lt_u32_e64 s[18:19], v5, v2
	v_or_b32_e32 v5, 26, v98
	s_and_b64 s[62:63], vcc, s[18:19]
	v_cmp_ge_u32_e32 vcc, v5, v6
	v_cmp_lt_u32_e64 s[18:19], v5, v2
	v_or_b32_e32 v5, 27, v98
	s_and_b64 s[64:65], vcc, s[18:19]
	v_cmp_ge_u32_e32 vcc, v5, v6
	v_cmp_lt_u32_e64 s[18:19], v5, v2
	v_or_b32_e32 v5, 32, v98
	s_and_b64 s[66:67], vcc, s[18:19]
	v_cmp_ge_u32_e32 vcc, v5, v6
	v_cmp_lt_u32_e64 s[18:19], v5, v2
	v_or_b32_e32 v5, 33, v98
	s_and_b64 s[68:69], vcc, s[18:19]
	v_cmp_ge_u32_e32 vcc, v5, v6
	v_cmp_lt_u32_e64 s[18:19], v5, v2
	v_or_b32_e32 v5, 34, v98
	s_and_b64 s[70:71], vcc, s[18:19]
	v_cmp_ge_u32_e32 vcc, v5, v6
	v_cmp_lt_u32_e64 s[18:19], v5, v2
	v_or_b32_e32 v5, 35, v98
	s_and_b64 s[72:73], vcc, s[18:19]
	v_cmp_ge_u32_e32 vcc, v5, v6
	v_cmp_lt_u32_e64 s[18:19], v5, v2
	v_or_b32_e32 v5, 40, v98
	s_and_b64 s[74:75], vcc, s[18:19]
	v_cmp_ge_u32_e32 vcc, v5, v6
	v_cmp_lt_u32_e64 s[18:19], v5, v2
	v_or_b32_e32 v5, 41, v98
	s_and_b64 s[76:77], vcc, s[18:19]
	v_cmp_ge_u32_e32 vcc, v5, v6
	v_cmp_lt_u32_e64 s[18:19], v5, v2
	v_or_b32_e32 v5, 42, v98
	s_and_b64 s[78:79], vcc, s[18:19]
	v_cmp_ge_u32_e32 vcc, v5, v6
	v_cmp_lt_u32_e64 s[18:19], v5, v2
	v_or_b32_e32 v5, 43, v98
	s_and_b64 s[38:39], vcc, s[18:19]
	v_cmp_ge_u32_e32 vcc, v5, v6
	v_cmp_lt_u32_e64 s[18:19], v5, v2
	v_or_b32_e32 v5, 48, v98
	s_and_b64 s[42:43], vcc, s[18:19]
	v_cmp_lt_u32_e64 s[18:19], v5, v2
	v_or_b32_e32 v5, 49, v98
	v_cmp_lt_u32_e64 s[20:21], v5, v2
	v_or_b32_e32 v5, 50, v98
	v_cmp_lt_u32_e64 s[22:23], v5, v2
	v_or_b32_e32 v5, 51, v98
	v_cmp_ge_u32_e64 s[2:3], v98, v6
	v_cmp_lt_u32_e64 s[24:25], v5, v2
	v_or_b32_e32 v5, 56, v98
	v_writelane_b32 v251, s2, 58
	v_cmp_lt_u32_e64 s[26:27], v5, v2
	v_or_b32_e32 v5, 57, v98
	v_lshlrev_b32_e32 v101, 7, v10
	v_writelane_b32 v251, s3, 59
	v_cmp_lt_u32_e64 s[28:29], v5, v2
	v_or_b32_e32 v5, 58, v98
	s_mov_b32 s2, 0x10000
	v_cmp_lt_u32_e64 s[30:31], v5, v2
	v_or_b32_e32 v5, 59, v98
	v_or3_b32 v114, v101, v4, s2
	s_add_i32 s2, s36, s94
	v_cmp_lt_u32_e64 s[34:35], v5, v2
	v_add_u32_e32 v2, s2, v10
	s_sub_i32 s90, s37, s44
	v_lshrrev_b32_e32 v2, 6, v2
	v_sub_u32_e32 v2, s90, v2
	s_movk_i32 s2, 0x7c
	v_mul_lo_u32 v2, v2, s2
	s_lshr_b32 s2, s49, 1
	s_and_b32 s2, s2, 0xffe0
	v_bitop3_b16 v4, s2, v8, 31 bitop3:0xf8
	v_and_b32_e32 v4, 63, v4
	v_lshl_add_u32 v2, v9, 4, v2
	v_lshlrev_b32_e32 v4, 2, v4
	v_sub_u32_e32 v2, v2, v4
	v_mov_b32_e32 v16, v3
	v_mov_b32_e32 v17, v3
	v_lshlrev_b32_e32 v106, 4, v7
	v_add_u32_e32 v115, 0x183a0, v2
	v_mov_b32_e32 v2, v3
	v_mov_b32_e32 v4, v3
	v_mov_b32_e32 v5, v3
	v_mov_b32_e32 v6, v3
	v_mov_b32_e32 v7, v3
	v_mov_b32_e32 v8, v3
	v_mov_b32_e32 v9, v3
	v_mov_b32_e32 v10, v3
	v_mov_b32_e32 v11, v3
	v_mov_b32_e32 v12, v3
	v_mov_b32_e32 v13, v3
	v_mov_b32_e32 v14, v3
	v_mov_b32_e32 v15, v3
	v_mov_b64_e32 v[34:35], v[16:17]
	v_mov_b64_e32 v[32:33], v[14:15]
	v_mov_b64_e32 v[30:31], v[12:13]
	v_mov_b64_e32 v[28:29], v[10:11]
	v_mov_b64_e32 v[26:27], v[8:9]
	v_mov_b64_e32 v[24:25], v[6:7]
	v_mov_b64_e32 v[22:23], v[4:5]
	v_mov_b64_e32 v[20:21], v[2:3]
	v_mov_b64_e32 v[18:19], v[16:17]
	s_add_i32 s40, s41, -3
	v_xor_b32_e32 v107, 16, v106
	v_xor_b32_e32 v108, 32, v106
	v_xor_b32_e32 v109, 48, v106
	v_xor_b32_e32 v110, 64, v106
	v_xor_b32_e32 v111, 0x50, v106
	v_xor_b32_e32 v112, 0x60, v106
	v_xor_b32_e32 v113, 0x70, v106
	s_add_i32 s41, s41, -1
	s_mov_b32 s49, 0
	v_mov_b32_e32 v94, 0xf149f2ca
	v_mov_b32_e32 v116, 0
	v_mov_b64_e32 v[16:17], v[14:15]
	v_mov_b64_e32 v[14:15], v[12:13]
	v_mov_b64_e32 v[12:13], v[10:11]
	v_mov_b64_e32 v[10:11], v[8:9]
	v_mov_b64_e32 v[8:9], v[6:7]
	v_mov_b64_e32 v[6:7], v[4:5]
	v_mov_b64_e32 v[4:5], v[2:3]
	v_mov_b32_e32 v194, 0
	v_mov_b32_e32 v195, 0
	v_mov_b32_e32 v196, 0
	v_mov_b32_e32 v197, 0
	v_mov_b32_e32 v198, 0
	v_mov_b32_e32 v199, 0
	v_mov_b32_e32 v200, 0
	v_mov_b32_e32 v201, 0
	v_mov_b32_e32 v202, 0
	v_mov_b32_e32 v203, 0
	v_mov_b32_e32 v204, 0
	v_mov_b32_e32 v205, 0
	v_mov_b32_e32 v206, 0
	v_mov_b32_e32 v207, 0
	v_mov_b32_e32 v208, 0
	v_mov_b32_e32 v209, 0
	v_mov_b32_e32 v210, 0
	v_mov_b32_e32 v211, 0
	v_mov_b32_e32 v212, 0
	v_mov_b32_e32 v213, 0
	v_mov_b32_e32 v214, 0
	v_mov_b32_e32 v215, 0
	v_mov_b32_e32 v216, 0
	v_mov_b32_e32 v217, 0
	s_waitcnt vmcnt(0)
	s_branch .LBB0_405

.Lat64_fast:
	s_cmp_eq_u64 s[46:47], 0
	s_cbranch_scc1 .Lat64_fastd
	s_and_b32 s2, s49, 3
	v_lshl_or_b32 v2, s2, 14, v101
	v_add_u32_e32 v36, v2, v102
	v_add_u32_e32 v37, v2, v103
	v_add_u32_e32 v38, v2, v104
	v_add_u32_e32 v39, v2, v105
	ds_read_b128 v[118:121], v36
	ds_read_b128 v[122:125], v37
	ds_read_b128 v[126:129], v38
	ds_read_b128 v[130:133], v39
	ds_read_b128 v[134:137], v36 offset:4096
	ds_read_b128 v[138:141], v37 offset:4096
	ds_read_b128 v[142:145], v38 offset:4096
	ds_read_b128 v[146:149], v39 offset:4096
	v_lshl_add_u32 v170, s2, 13, v114
	s_waitcnt lgkmcnt(7)
	v_mfma_f32_32x32x16_bf16 v[52:67], v[118:121], v[68:71], 0
	s_waitcnt lgkmcnt(6)
	v_mfma_f32_32x32x16_bf16 v[52:67], v[122:125], v[72:75], v[52:67]
	s_waitcnt lgkmcnt(5)
	v_mfma_f32_32x32x16_bf16 v[52:67], v[126:129], v[76:79], v[52:67]
	s_waitcnt lgkmcnt(4)
	v_mfma_f32_32x32x16_bf16 v[52:67], v[130:133], v[80:83], v[52:67]
	s_waitcnt lgkmcnt(0)
	v_mfma_f32_32x32x16_bf16 v[36:51], v[134:137], v[68:71], 0
	v_add_u32_e32 v154, v170, v106
	v_add_u32_e32 v155, v170, v107
	ds_read_b64 v[118:119], v154
	ds_read_b64 v[120:121], v155
	v_mfma_f32_32x32x16_bf16 v[36:51], v[138:141], v[72:75], v[36:51]
	v_add_u32_e32 v156, v170, v108
	v_add_u32_e32 v157, v170, v109
	ds_read_b64 v[122:123], v156
	ds_read_b64 v[124:125], v157
	v_mfma_f32_32x32x16_bf16 v[36:51], v[142:145], v[76:79], v[36:51]
	v_add_u32_e32 v158, v170, v110
	v_add_u32_e32 v159, v170, v111
	ds_read_b64 v[126:127], v158
	ds_read_b64 v[128:129], v159
	v_mfma_f32_32x32x16_bf16 v[36:51], v[146:149], v[80:83], v[36:51]
	v_add_u32_e32 v160, v170, v112
	v_add_u32_e32 v161, v170, v113
	ds_read_b64 v[130:131], v160
	ds_read_b64 v[132:133], v161
	ds_read_b64 v[142:143], v158 offset:4096
	ds_read_b64 v[144:145], v159 offset:4096
	ds_read_b64 v[146:147], v160 offset:4096
	ds_read_b64 v[148:149], v161 offset:4096
	ds_read_b64 v[138:139], v156 offset:4096
	ds_read_b64 v[140:141], v157 offset:4096
	ds_read_b64 v[134:135], v154 offset:4096
	ds_read_b64 v[136:137], v155 offset:4096
	v_max3_f32 v2, v52, v53, v54
	v_max3_f32 v2, v2, v55, v56
	v_max3_f32 v2, v2, v57, v58
	v_max3_f32 v2, v2, v59, v60
	v_max3_f32 v2, v2, v61, v62
	v_max3_f32 v2, v2, v63, v64
	v_max3_f32 v2, v2, v65, v66
	v_max_f32_e32 v2, v2, v67
	v_max3_f32 v170, v36, v37, v38
	v_max3_f32 v170, v170, v39, v40
	v_max3_f32 v170, v170, v41, v42
	v_max3_f32 v170, v170, v43, v44
	v_max3_f32 v170, v170, v45, v46
	v_max3_f32 v170, v170, v47, v48
	v_max3_f32 v170, v170, v49, v50
	v_max3_f32 v2, v2, v170, v51
	s_mov_b32 s3, 0x3e38aa3b
	v_mul_f32_e32 v2, s3, v2
	v_mov_b32_e32 v167, v2
	s_nop 1
	v_permlane32_swap_b32 v2, v167
	s_nop 1
	v_max3_f32 v166, v94, v2, v167
	v_sub_f32_e32 v168, v94, v166
	v_exp_f32_e32 v168, v168
	v_cmp_neq_f32_e32 vcc, v166, v94
	s_cbranch_vccz .Lat64_keep
	v_pk_mul_f32 v[34:35], v[34:35], v[168:169] op_sel_hi:[1,0]
	v_pk_mul_f32 v[32:33], v[32:33], v[168:169] op_sel_hi:[1,0]
	v_pk_mul_f32 v[30:31], v[30:31], v[168:169] op_sel_hi:[1,0]
	v_pk_mul_f32 v[28:29], v[28:29], v[168:169] op_sel_hi:[1,0]
	v_pk_mul_f32 v[26:27], v[26:27], v[168:169] op_sel_hi:[1,0]
	v_pk_mul_f32 v[24:25], v[24:25], v[168:169] op_sel_hi:[1,0]
	v_pk_mul_f32 v[22:23], v[22:23], v[168:169] op_sel_hi:[1,0]
	v_pk_mul_f32 v[20:21], v[20:21], v[168:169] op_sel_hi:[1,0]
	v_pk_mul_f32 v[18:19], v[18:19], v[168:169] op_sel_hi:[1,0]
	v_pk_mul_f32 v[16:17], v[16:17], v[168:169] op_sel_hi:[1,0]
	v_pk_mul_f32 v[14:15], v[14:15], v[168:169] op_sel_hi:[1,0]
	v_pk_mul_f32 v[12:13], v[12:13], v[168:169] op_sel_hi:[1,0]
	v_pk_mul_f32 v[10:11], v[10:11], v[168:169] op_sel_hi:[1,0]
	v_pk_mul_f32 v[8:9], v[8:9], v[168:169] op_sel_hi:[1,0]
	v_pk_mul_f32 v[6:7], v[6:7], v[168:169] op_sel_hi:[1,0]
	v_pk_mul_f32 v[4:5], v[4:5], v[168:169] op_sel_hi:[1,0]

.Lat64_fastd:
	s_and_b32 s2, s49, 3
	v_lshl_or_b32 v2, s2, 14, v101
	v_add_u32_e32 v36, v2, v102
	v_add_u32_e32 v37, v2, v103
	v_add_u32_e32 v38, v2, v104
	v_add_u32_e32 v39, v2, v105
	ds_read_b128 v[118:121], v36
	ds_read_b128 v[122:125], v37
	ds_read_b128 v[126:129], v38
	ds_read_b128 v[130:133], v39
	ds_read_b128 v[134:137], v36 offset:4096
	ds_read_b128 v[138:141], v37 offset:4096
	ds_read_b128 v[142:145], v38 offset:4096
	ds_read_b128 v[146:149], v39 offset:4096
	v_lshl_add_u32 v170, s2, 13, v114
	v_mfma_f32_32x32x16_bf16 v[20:35], v[194:197], v[210:213], v[20:35]
	v_mfma_f32_32x32x16_bf16 v[4:19], v[202:205], v[210:213], v[4:19]
	v_mfma_f32_32x32x16_bf16 v[20:35], v[198:201], v[214:217], v[20:35]
	v_mfma_f32_32x32x16_bf16 v[4:19], v[206:209], v[214:217], v[4:19]
	s_waitcnt lgkmcnt(7)
	v_mfma_f32_32x32x16_bf16 v[52:67], v[118:121], v[68:71], 0
	s_waitcnt lgkmcnt(6)
	v_mfma_f32_32x32x16_bf16 v[52:67], v[122:125], v[72:75], v[52:67]
	s_waitcnt lgkmcnt(5)
	v_mfma_f32_32x32x16_bf16 v[52:67], v[126:129], v[76:79], v[52:67]
	s_waitcnt lgkmcnt(4)
	v_mfma_f32_32x32x16_bf16 v[52:67], v[130:133], v[80:83], v[52:67]
	s_waitcnt lgkmcnt(0)
	v_mfma_f32_32x32x16_bf16 v[36:51], v[134:137], v[68:71], 0
	v_add_u32_e32 v154, v170, v106
	v_add_u32_e32 v155, v170, v107
	ds_read_b64 v[118:119], v154
	ds_read_b64 v[120:121], v155
	v_mfma_f32_32x32x16_bf16 v[36:51], v[138:141], v[72:75], v[36:51]
	v_add_u32_e32 v156, v170, v108
	v_add_u32_e32 v157, v170, v109
	ds_read_b64 v[122:123], v156
	ds_read_b64 v[124:125], v157
	v_mfma_f32_32x32x16_bf16 v[36:51], v[142:145], v[76:79], v[36:51]
	v_add_u32_e32 v158, v170, v110
	v_add_u32_e32 v159, v170, v111
	ds_read_b64 v[194:195], v158
	ds_read_b64 v[196:197], v159
	v_mfma_f32_32x32x16_bf16 v[36:51], v[146:149], v[80:83], v[36:51]
	v_add_u32_e32 v160, v170, v112
	v_add_u32_e32 v161, v170, v113
	ds_read_b64 v[198:199], v160
	ds_read_b64 v[200:201], v161
	ds_read_b64 v[202:203], v158 offset:4096
	ds_read_b64 v[204:205], v159 offset:4096
	ds_read_b64 v[206:207], v160 offset:4096
	ds_read_b64 v[208:209], v161 offset:4096
	ds_read_b64 v[138:139], v156 offset:4096
	ds_read_b64 v[140:141], v157 offset:4096
	ds_read_b64 v[134:135], v154 offset:4096
	ds_read_b64 v[136:137], v155 offset:4096
	v_max3_f32 v2, v52, v53, v54
	v_max3_f32 v2, v2, v55, v56
	v_max3_f32 v2, v2, v57, v58
	v_max3_f32 v2, v2, v59, v60
	v_max3_f32 v2, v2, v61, v62
	v_max3_f32 v2, v2, v63, v64
	v_max3_f32 v2, v2, v65, v66
	v_max_f32_e32 v2, v2, v67
	v_max3_f32 v170, v36, v37, v38
	v_max3_f32 v170, v170, v39, v40
	v_max3_f32 v170, v170, v41, v42
	v_max3_f32 v170, v170, v43, v44
	v_max3_f32 v170, v170, v45, v46
	v_max3_f32 v170, v170, v47, v48
	v_max3_f32 v170, v170, v49, v50
	v_max3_f32 v2, v2, v170, v51
	s_mov_b32 s3, 0x3e38aa3b
	v_mul_f32_e32 v2, s3, v2
	v_mov_b32_e32 v167, v2
	s_nop 1
	v_permlane32_swap_b32 v2, v167
	s_nop 1
	v_max3_f32 v166, v94, v2, v167
	v_sub_f32_e32 v168, v94, v166
	v_exp_f32_e32 v168, v168
	v_cmp_neq_f32_e32 vcc, v166, v94
	s_cbranch_vccz .Lat64d_keep
	v_pk_mul_f32 v[34:35], v[34:35], v[168:169] op_sel_hi:[1,0]
	v_pk_mul_f32 v[32:33], v[32:33], v[168:169] op_sel_hi:[1,0]
	v_pk_mul_f32 v[30:31], v[30:31], v[168:169] op_sel_hi:[1,0]
	v_pk_mul_f32 v[28:29], v[28:29], v[168:169] op_sel_hi:[1,0]
	v_pk_mul_f32 v[26:27], v[26:27], v[168:169] op_sel_hi:[1,0]
	v_pk_mul_f32 v[24:25], v[24:25], v[168:169] op_sel_hi:[1,0]
	v_pk_mul_f32 v[22:23], v[22:23], v[168:169] op_sel_hi:[1,0]
	v_pk_mul_f32 v[20:21], v[20:21], v[168:169] op_sel_hi:[1,0]
	v_pk_mul_f32 v[18:19], v[18:19], v[168:169] op_sel_hi:[1,0]
	v_pk_mul_f32 v[16:17], v[16:17], v[168:169] op_sel_hi:[1,0]
	v_pk_mul_f32 v[14:15], v[14:15], v[168:169] op_sel_hi:[1,0]
	v_pk_mul_f32 v[12:13], v[12:13], v[168:169] op_sel_hi:[1,0]
	v_pk_mul_f32 v[10:11], v[10:11], v[168:169] op_sel_hi:[1,0]
	v_pk_mul_f32 v[8:9], v[8:9], v[168:169] op_sel_hi:[1,0]
	v_pk_mul_f32 v[6:7], v[6:7], v[168:169] op_sel_hi:[1,0]
	v_pk_mul_f32 v[4:5], v[4:5], v[168:169] op_sel_hi:[1,0]
.Lat64d_keep:
	v_fma_f32 v52, v52, s3, -v166
	v_fma_f32 v53, v53, s3, -v166
	v_fma_f32 v54, v54, s3, -v166
	v_fma_f32 v55, v55, s3, -v166
	v_fma_f32 v56, v56, s3, -v166
	v_fma_f32 v57, v57, s3, -v166
	v_fma_f32 v58, v58, s3, -v166
	v_fma_f32 v59, v59, s3, -v166
	v_exp_f32_e32 v52, v52
	v_exp_f32_e32 v53, v53
	v_exp_f32_e32 v54, v54
	v_exp_f32_e32 v55, v55
	v_exp_f32_e32 v56, v56
	v_exp_f32_e32 v57, v57
	v_exp_f32_e32 v58, v58
	v_exp_f32_e32 v59, v59
	v_cvt_pk_bf16_f32 v150, v52, v53
	v_cvt_pk_bf16_f32 v151, v54, v55
	v_cvt_pk_bf16_f32 v152, v56, v57
	v_cvt_pk_bf16_f32 v153, v58, v59
	v_add_f32_e32 v52, v52, v53
	v_add_f32_e32 v54, v54, v55
	v_add_f32_e32 v56, v56, v57
	v_add_f32_e32 v58, v58, v59
	v_add_f32_e32 v52, v52, v54
	v_add_f32_e32 v56, v56, v58
	v_add_f32_e32 v52, v52, v56
	v_fma_f32 v60, v60, s3, -v166
	v_fma_f32 v61, v61, s3, -v166
	v_fma_f32 v62, v62, s3, -v166
	v_fma_f32 v63, v63, s3, -v166
	v_fma_f32 v64, v64, s3, -v166
	v_fma_f32 v65, v65, s3, -v166
	v_fma_f32 v66, v66, s3, -v166
	v_fma_f32 v67, v67, s3, -v166
	v_exp_f32_e32 v60, v60
	v_exp_f32_e32 v61, v61
	v_exp_f32_e32 v62, v62
	v_exp_f32_e32 v63, v63
	v_exp_f32_e32 v64, v64
	v_exp_f32_e32 v65, v65
	v_exp_f32_e32 v66, v66
	v_exp_f32_e32 v67, v67
	v_cvt_pk_bf16_f32 v154, v60, v61
	v_cvt_pk_bf16_f32 v155, v62, v63
	v_cvt_pk_bf16_f32 v156, v64, v65
	v_cvt_pk_bf16_f32 v157, v66, v67
	v_add_f32_e32 v60, v60, v61
	v_add_f32_e32 v62, v62, v63
	v_add_f32_e32 v64, v64, v65
	v_add_f32_e32 v66, v66, v67
	v_add_f32_e32 v60, v60, v62
	v_add_f32_e32 v64, v64, v66
	v_add_f32_e32 v60, v60, v64
	s_waitcnt lgkmcnt(0)
	v_mfma_f32_32x32x16_bf16 v[20:35], v[118:121], v[150:153], v[20:35]
	v_fma_f32 v36, v36, s3, -v166
	v_fma_f32 v37, v37, s3, -v166
	v_fma_f32 v38, v38, s3, -v166
	v_fma_f32 v39, v39, s3, -v166
	v_fma_f32 v40, v40, s3, -v166
	v_fma_f32 v41, v41, s3, -v166
	v_fma_f32 v42, v42, s3, -v166
	v_fma_f32 v43, v43, s3, -v166
	v_mfma_f32_32x32x16_bf16 v[4:19], v[134:137], v[150:153], v[4:19]
	v_exp_f32_e32 v36, v36
	v_exp_f32_e32 v37, v37
	v_exp_f32_e32 v38, v38
	v_exp_f32_e32 v39, v39
	v_exp_f32_e32 v40, v40
	v_exp_f32_e32 v41, v41
	v_exp_f32_e32 v42, v42
	v_exp_f32_e32 v43, v43
	v_mfma_f32_32x32x16_bf16 v[20:35], v[122:125], v[154:157], v[20:35]
	v_cvt_pk_bf16_f32 v210, v36, v37
	v_cvt_pk_bf16_f32 v211, v38, v39
	v_cvt_pk_bf16_f32 v212, v40, v41
	v_cvt_pk_bf16_f32 v213, v42, v43
	v_add_f32_e32 v36, v36, v37
	v_add_f32_e32 v38, v38, v39
	v_add_f32_e32 v40, v40, v41
	v_add_f32_e32 v42, v42, v43
	v_add_f32_e32 v36, v36, v38
	v_add_f32_e32 v40, v40, v42
	v_add_f32_e32 v36, v36, v40
	v_mfma_f32_32x32x16_bf16 v[4:19], v[138:141], v[154:157], v[4:19]
	v_fma_f32 v44, v44, s3, -v166
	v_fma_f32 v45, v45, s3, -v166
	v_fma_f32 v46, v46, s3, -v166
	v_fma_f32 v47, v47, s3, -v166
	v_fma_f32 v48, v48, s3, -v166
	v_fma_f32 v49, v49, s3, -v166
	v_fma_f32 v50, v50, s3, -v166
	v_fma_f32 v51, v51, s3, -v166
	v_exp_f32_e32 v44, v44
	v_exp_f32_e32 v45, v45
	v_exp_f32_e32 v46, v46
	v_exp_f32_e32 v47, v47
	v_exp_f32_e32 v48, v48
	v_exp_f32_e32 v49, v49
	v_exp_f32_e32 v50, v50
	v_exp_f32_e32 v51, v51
	v_cvt_pk_bf16_f32 v214, v44, v45
	v_cvt_pk_bf16_f32 v215, v46, v47
	v_cvt_pk_bf16_f32 v216, v48, v49
	v_cvt_pk_bf16_f32 v217, v50, v51
	v_add_f32_e32 v44, v44, v45
	v_add_f32_e32 v46, v46, v47
	v_add_f32_e32 v48, v48, v49
	v_add_f32_e32 v50, v50, v51
	v_add_f32_e32 v44, v44, v46
	v_add_f32_e32 v48, v48, v50
	v_add_f32_e32 v44, v44, v48
	v_add_f32_e32 v52, v52, v60
	v_add_f32_e32 v36, v36, v44
	v_add_f32_e32 v52, v52, v36
	v_fma_f32 v116, v116, v168, v52
	v_mov_b32_e32 v94, v166
	s_branch .LBB0_404
.LBB0_488:
	s_cmp_lg_u64 s[46:47], 0
	s_cbranch_scc1 .Lat64_noflush
	v_mfma_f32_32x32x16_bf16 v[20:35], v[194:197], v[210:213], v[20:35]
	v_mfma_f32_32x32x16_bf16 v[4:19], v[202:205], v[210:213], v[4:19]
	v_mfma_f32_32x32x16_bf16 v[20:35], v[198:201], v[214:217], v[20:35]
	v_mfma_f32_32x32x16_bf16 v[4:19], v[206:209], v[214:217], v[4:19]
